# ml_local gate loads: all 6 gate loads issued together after the hoisted conv loads, single wait
# baseline (speedup 1.0000x reference)
; #define LAS __attribute__((address_space(3)))
; DEV bf16x8 pack8(const float* x) { u32x4 o; o.x = pk2(x[0], x[1]); o.y = pk2(x[2], x[3]); o.z = pk2(x[4], x[5]); o.w = pk2(x[6], x[7]); return __builtin_bit_cast(bf16x8, o); }
; DEV GateRaw ml_gates_load(const Fr& F, int l, int row0, int h, int dir, int lane) {
;     const int u0 = 2 * lane, u1 = u0 + 1; const int s0 = dir ? 127 - u0 : u0, s1 = dir ? 127 - u1 : u1;
;     const float bi = F.in[I_GATEB][l * 16 + (dir * 2) * 4 + h], bf = F.in[I_GATEB][l * 16 + (dir * 2 + 1) * 4 + h];
;     const bf16_t* z0 = F.Z + (size_t)(row0 + s0) * ZS + ZC_MG, * z1 = F.Z + (size_t)(row0 + s1) * ZS + ZC_MG;
;     GateRaw r; r.li0 = bf2f(z0[(dir * 2) * 4 + h]) + bi; r.li1 = bf2f(z1[(dir * 2) * 4 + h]) + bi;
;     r.lp0 = bf2f(z0[(dir * 2 + 1) * 4 + h]) + bf; r.lp1 = bf2f(z1[(dir * 2 + 1) * 4 + h]) + bf; return r;
; }
; DEV void ml_local_item(const Fr& F, int l, int b, int ch, int h) {
;     LAS bf16_t* Vs = (LAS bf16_t*)F.lds;
;     LAS bf16_t* KTf = Vs + 128 * 72;
;     LAS bf16_t* KTb = KTf + 128 * 72;
;     LAS float* wv = (LAS float*)(KTb + 128 * 72);
;     const int tid = F.tid, w = F.wave, lane = F.lane, fr = lane & 15, fq = lane >> 4;
;     const bool isctx = ch < 2; const int seqlen = isctx ? CTXL : SEQ; const int p0 = isctx ? ch * 128 : (ch - 2) * 128;
;     const int seqrow0 = b * RPB + (isctx ? 0 : CTXL); const int row0 = b * RPB + ch * 128;
;     GateRaw graw; graw.li0 = graw.li1 = graw.lp0 = graw.lp1 = 0.f;
;     if (w < 2) graw = ml_gates_load(F, l, row0, h, w, lane);
;     u32x4 vv[2]; float kk[2][8];
; #pragma unroll
;     for (int i = 0; i < 2; ++i) { const int idx = tid + NTHR * i; const int s = idx >> 3, c8 = (idx & 7) * 8;
;         vv[i] = *(const u32x4*)(F.Z + (size_t)(row0 + s) * ZS + ZC_MV + h * 64 + c8);
;         conv_silu8(F, seqrow0, seqlen, p0 + s, ZC_MK + h * 64 + c8, F.in[I_CONVW] + l * 1536 + 256 + h * 64 + c8, 0.125f, kk[i]);
;         *(bf16x8*)(F.A + (size_t)(row0 + s) * 256 + h * 64 + c8) = pack8(kk[i]); }
.LBB0_314:
	s_mul_hi_i32 s4, s25, 0x7e07e07f
	s_lshr_b32 s5, s4, 31
	s_ashr_i32 s19, s4, 8
	s_ashr_i32 s4, s25, 2
	s_add_i32 s19, s19, s5
	s_mul_hi_i32 s5, s4, 0x7e07e07f
	s_lshr_b32 s6, s5, 31
	s_ashr_i32 s5, s5, 6
	s_add_i32 s5, s5, s6
	s_mulk_i32 s5, 0x82
	s_sub_i32 s18, s4, s5
	s_lshl_b32 s7, s18, 7
	s_mul_i32 s6, s19, 0x4100
	v_cndmask_b32_e64 v2, 0, 1, s[16:17]
	s_and_b32 s26, s25, 3
	s_add_i32 s29, s7, s6
	v_mov_b32_e32 v32, 0
	v_cmp_ne_u32_e64 s[4:5], 1, v2
	s_andn2_b64 vcc, exec, s[16:17]
	v_mov_b32_e32 v12, 0
	v_mov_b32_e32 v13, 0
	v_mov_b32_e32 v10, 0
	v_mov_b32_e32 v11, 0
.LBB0_316:
	s_add_i32 s8, s7, 0xffffff00
	s_cmp_lt_i32 s18, 2
	s_movk_i32 s9, 0x4000
	v_add_u32_e32 v6, s29, v48
	v_mov_b64_e32 v[2:3], s[78:79]
	s_cselect_b32 s27, 0x100, s9
	s_cselect_b32 s30, 0, 0x100
	s_cselect_b32 s31, s7, s8
	v_mad_i64_i32 v[2:3], s[8:9], v6, s53, v[2:3]
	s_lshl_b32 s60, s26, 7
	v_lshl_add_u64 v[2:3], v[2:3], 0, s[60:61]
	v_mov_b32_e32 v31, v0
	v_lshl_add_u64 v[2:3], v[2:3], 0, v[30:31]
	global_load_dwordx4 v[2:5], v[2:3], off offset:2048
	s_lshl_b32 s33, s26, 6
	v_or_b32_e32 v8, s33, v18
	v_add_u32_e32 v7, s31, v48
	s_add_i32 s30, s30, s6
	s_lshl_b32 s60, s26, 8
	v_lshlrev_b32_e32 v8, 1, v8
	v_mov_b32_e32 v9, v0
	v_cmp_lt_i32_e32 vcc, 0, v7
	v_cmp_ge_i32_e64 s[8:9], s27, v7
	s_add_i32 s28, s30, -1
	v_lshl_add_u64 v[16:17], v[20:21], 0, s[60:61]
	v_lshl_add_u64 v[14:15], s[78:79], 0, v[8:9]
	s_and_b64 s[8:9], vcc, s[8:9]
	v_mov_b32_e32 v33, 0
	v_mov_b32_e32 v38, 0
	v_mov_b32_e32 v39, 0
	v_mov_b32_e32 v36, 0
	v_mov_b32_e32 v37, 0
	v_mov_b32_e32 v8, 0
	v_mov_b32_e32 v9, 0
	v_mov_b32_e32 v40, 0
	v_mov_b32_e32 v41, 0
	v_add_u32_e32 v243, s31, v49
	global_load_dwordx4 v[156:159], v[16:17], off offset:1024
	global_load_dwordx4 v[160:163], v[16:17], off offset:1040
	global_load_dwordx4 v[164:167], v[16:17], off offset:3072
	global_load_dwordx4 v[168:171], v[16:17], off offset:3088
	s_mov_b64 s[100:101], 0x1000
	v_lshl_add_u64 v[244:245], v[16:17], 0, s[100:101]
	global_load_dwordx4 v[172:175], v[244:245], off offset:1024
	global_load_dwordx4 v[176:179], v[244:245], off offset:1040
	v_cmp_lt_i32_e32 vcc, 0, v7
	v_cmp_ge_i32_e64 s[100:101], s27, v7
	s_and_b64 vcc, vcc, s[100:101]
	s_and_saveexec_b64 s[100:101], vcc
	s_cbranch_execz .Lmlc_a0
	v_add_u32_e32 v246, s28, v7
	v_mad_i64_i32 v[246:247], vcc, v246, s53, v[14:15]
	global_load_dwordx4 v[180:183], v[246:247], off offset:1536

; DEV GateRaw ml_gates_load(const Fr& F, int l, int row0, int h, int dir, int lane) {
;     const int u0 = 2 * lane, u1 = u0 + 1; const int s0 = dir ? 127 - u0 : u0, s1 = dir ? 127 - u1 : u1;
;     const float bi = F.in[I_GATEB][l * 16 + (dir * 2) * 4 + h], bf = F.in[I_GATEB][l * 16 + (dir * 2 + 1) * 4 + h];
;     const bf16_t* z0 = F.Z + (size_t)(row0 + s0) * ZS + ZC_MG, * z1 = F.Z + (size_t)(row0 + s1) * ZS + ZC_MG;
;     GateRaw r; r.li0 = bf2f(z0[(dir * 2) * 4 + h]) + bi; r.li1 = bf2f(z1[(dir * 2) * 4 + h]) + bi;
;     r.lp0 = bf2f(z0[(dir * 2 + 1) * 4 + h]) + bf; r.lp1 = bf2f(z1[(dir * 2 + 1) * 4 + h]) + bf; return r;
; }
; DEV void conv_silu8(const Fr& F, int seqrow0, int seqlen, int p, int zc, const float* cw, float scale, float* o) {
;     ...
;     for (int tap = 0; tap < 3; ++tap) { const int pp = p + tap - 1; if (pp >= 0 && pp < seqlen) { unpack8(*(const u32x4*)(F.Z + (size_t)(seqrow0 + pp) * ZS + zc), x);
;         const f32x4 w0 = *(const f32x4*)(cw + tap * 512), w1 = *(const f32x4*)(cw + tap * 512 + 4);
; #pragma unroll
;         for (int j = 0; j < 4; ++j) { a[j] += x[j] * w0[j]; a[4 + j] += x[4 + j] * w1[j]; } } }
.Lmlc_b2:
	s_or_b64 exec, exec, s[100:101]
	s_andn2_b64 vcc, exec, s[16:17]
	s_cbranch_vccnz .Lmlg_skip
	s_or_b32 s100, s20, s26
	s_ashr_i32 s101, s100, 31
	s_lshl_b64 s[100:101], s[100:101], 2
	v_readlane_b32 s44, v242, 18
	v_readlane_b32 s45, v242, 19
	s_nop 0
	s_add_u32 s100, s44, s100
	s_addc_u32 s101, s45, s101
	global_load_dword v248, v0, s[100:101]
	s_add_u32 s100, s23, s26
	s_addc_u32 s101, s24, 0
	s_lshl_b64 s[100:101], s[100:101], 2
	s_add_u32 s100, s44, s100
	s_addc_u32 s101, s45, s101
	global_load_dword v249, v0, s[100:101] offset:16
	v_or_b32_e32 v250, s29, v1
	v_mov_b64_e32 v[246:247], s[78:79]
	v_mad_i64_i32 v[244:245], vcc, v250, s53, v[246:247]
	v_or_b32_e32 v250, s29, v19
	v_mad_i64_i32 v[246:247], vcc, v250, s53, v[246:247]
	s_or_b32 s100, s15, s26
	s_ashr_i32 s101, s100, 31
	s_lshl_b64 s[100:101], s[100:101], 1
	v_lshl_add_u64 v[254:255], v[246:247], 0, s[100:101]
	global_load_ushort v250, v[254:255], off offset:3072
	v_lshl_add_u64 v[254:255], v[244:245], 0, s[100:101]
	global_load_ushort v251, v[254:255], off offset:3072
	s_add_u32 s100, s15, s26
	s_addc_u32 s101, s22, 0
	s_lshl_b64 s[100:101], s[100:101], 1
	v_lshl_add_u64 v[254:255], v[246:247], 0, s[100:101]
	global_load_ushort v252, v[254:255], off offset:3080
	v_lshl_add_u64 v[254:255], v[244:245], 0, s[100:101]
	global_load_ushort v253, v[254:255], off offset:3080
	v_readlane_b32 s36, v242, 10
	v_readlane_b32 s37, v242, 11
	v_readlane_b32 s38, v242, 12
	v_readlane_b32 s39, v242, 13
	v_readlane_b32 s40, v242, 14
	v_readlane_b32 s41, v242, 15
	v_readlane_b32 s42, v242, 16
	v_readlane_b32 s43, v242, 17
	v_readlane_b32 s46, v242, 20
	v_readlane_b32 s47, v242, 21
	v_readlane_b32 s48, v242, 22
	v_readlane_b32 s49, v242, 23
	v_readlane_b32 s50, v242, 24
	v_readlane_b32 s51, v242, 25
	s_waitcnt vmcnt(0)
	v_lshlrev_b32_e32 v250, 16, v250
	v_lshlrev_b32_e32 v251, 16, v251
	v_lshlrev_b32_e32 v252, 16, v252
	v_lshlrev_b32_e32 v253, 16, v253
	v_add_f32_e32 v10, v248, v250
	v_add_f32_e32 v11, v248, v251
	v_add_f32_e32 v12, v249, v252
	v_add_f32_e32 v13, v249, v253
.Lmlg_skip:
	s_waitcnt vmcnt(0)
	s_and_saveexec_b64 s[6:7], s[8:9]
	s_cbranch_execz .LBB0_318
	v_lshlrev_b32_e32 v8, 16, v180
	v_and_b32_e32 v9, 0xffff0000, v180
	v_lshlrev_b32_e32 v32, 16, v181
	v_and_b32_e32 v33, 0xffff0000, v181
	v_pk_fma_f32 v[36:37], v[158:159], v[32:33], 0 op_sel_hi:[1,1,0]
	v_lshlrev_b32_e32 v32, 16, v183
	v_and_b32_e32 v33, 0xffff0000, v183
	v_pk_fma_f32 v[38:39], v[156:157], v[8:9], 0 op_sel_hi:[1,1,0]
	v_lshlrev_b32_e32 v8, 16, v182
	v_and_b32_e32 v9, 0xffff0000, v182
	v_pk_fma_f32 v[32:33], v[162:163], v[32:33], 0 op_sel_hi:[1,1,0]
	v_pk_fma_f32 v[8:9], v[160:161], v[8:9], 0 op_sel_hi:[1,1,0]
	v_mov_b32_e32 v40, v32
	v_mov_b32_e32 v41, v33
